# P4 epilogue touches the next tile's first two K-tiles of A (L2 warm-up for the next prologue)
# speedup vs baseline: 1.0089x; 1.0072x over previous
.LBB0_24:
	ds_read_b128 v[154:157], v138
	ds_read_b128 v[158:161], v139
	ds_read_b128 v[162:165], v140
	ds_read_b128 v[194:197], v141
	ds_read_b128 v[198:201], v142
	ds_read_b128 v[202:205], v143
	ds_read_b128 v[206:209], v144
	ds_read_b128 v[210:213], v145
	s_add_u32 s14, s96, s88
	s_addc_u32 s15, s97, s89
	s_add_u32 s14, s14, 0x4000900
	s_addc_u32 s15, s15, 0
	s_add_u32 s36, s42, s88
	s_addc_u32 s37, s43, s89
	s_cmpk_eq_i32 s88, 0x700
	s_cselect_b32 s27, s87, s15
	s_cselect_b32 s26, s86, s14
	s_cselect_b32 s15, s85, s37
	s_cselect_b32 s14, s84, s36
	v_lshl_add_u64 v[166:167], v[130:131], 0, s[88:89]
	s_add_i32 m0, s94, 0xc000
	ds_read_b128 v[214:217], v137
	ds_read_b128 v[218:221], v137 offset:1024
	ds_read_b128 v[222:225], v137 offset:2048
	ds_read_b128 v[226:229], v137 offset:3072
	ds_read_b128 v[230:233], v137 offset:4096
	ds_read_b128 v[234:237], v137 offset:5120
	ds_read_b128 v[238:241], v137 offset:6144
	ds_read_b128 v[242:245], v137 offset:7168
	global_load_lds_dwordx4 v[166:167], off
	v_lshl_add_u64 v[166:167], v[132:133], 0, s[88:89]
	s_mov_b32 m0, s48
	s_nop 0
	global_load_lds_dwordx4 v[166:167], off
	s_waitcnt vmcnt(8)
	s_waitcnt lgkmcnt(0)
	s_barrier
	s_setprio 1
	s_waitcnt lgkmcnt(0)
	v_mfma_f32_16x16x32_bf16 v[124:127], v[154:157], v[214:217], v[124:127]
	v_mfma_f32_16x16x32_bf16 v[120:123], v[162:165], v[214:217], v[120:123]
	v_mfma_f32_16x16x32_bf16 v[116:119], v[154:157], v[222:225], v[116:119]
	v_mfma_f32_16x16x32_bf16 v[112:115], v[162:165], v[222:225], v[112:115]
	v_mfma_f32_16x16x32_bf16 v[108:111], v[154:157], v[230:233], v[108:111]
	v_mfma_f32_16x16x32_bf16 v[104:107], v[162:165], v[230:233], v[104:107]
	v_mfma_f32_16x16x32_bf16 v[76:79], v[154:157], v[238:241], v[76:79]
	v_mfma_f32_16x16x32_bf16 v[72:75], v[162:165], v[238:241], v[72:75]
	v_mfma_f32_16x16x32_bf16 v[124:127], v[158:161], v[218:221], v[124:127]
	v_mfma_f32_16x16x32_bf16 v[120:123], v[194:197], v[218:221], v[120:123]
	v_mfma_f32_16x16x32_bf16 v[116:119], v[158:161], v[226:229], v[116:119]
	v_mfma_f32_16x16x32_bf16 v[112:115], v[194:197], v[226:229], v[112:115]
	v_mfma_f32_16x16x32_bf16 v[108:111], v[158:161], v[234:237], v[108:111]
	v_mfma_f32_16x16x32_bf16 v[104:107], v[194:197], v[234:237], v[104:107]
	v_mfma_f32_16x16x32_bf16 v[76:79], v[158:161], v[242:245], v[76:79]
	v_mfma_f32_16x16x32_bf16 v[72:75], v[194:197], v[242:245], v[72:75]
	s_setprio 0
	s_setprio 1
	v_mfma_f32_16x16x32_bf16 v[100:103], v[198:201], v[214:217], v[100:103]
	v_mfma_f32_16x16x32_bf16 v[96:99], v[206:209], v[214:217], v[96:99]
	v_mfma_f32_16x16x32_bf16 v[92:95], v[198:201], v[222:225], v[92:95]
	v_mfma_f32_16x16x32_bf16 v[88:91], v[206:209], v[222:225], v[88:91]
	v_mfma_f32_16x16x32_bf16 v[84:87], v[198:201], v[230:233], v[84:87]
	v_mfma_f32_16x16x32_bf16 v[80:83], v[206:209], v[230:233], v[80:83]
	v_mfma_f32_16x16x32_bf16 v[52:55], v[198:201], v[238:241], v[52:55]
	v_mfma_f32_16x16x32_bf16 v[44:47], v[206:209], v[238:241], v[44:47]
	v_mfma_f32_16x16x32_bf16 v[100:103], v[202:205], v[218:221], v[100:103]
	v_mfma_f32_16x16x32_bf16 v[96:99], v[210:213], v[218:221], v[96:99]
	v_mfma_f32_16x16x32_bf16 v[92:95], v[202:205], v[226:229], v[92:95]
	v_mfma_f32_16x16x32_bf16 v[88:91], v[210:213], v[226:229], v[88:91]
	v_mfma_f32_16x16x32_bf16 v[84:87], v[202:205], v[234:237], v[84:87]
	v_mfma_f32_16x16x32_bf16 v[80:83], v[210:213], v[234:237], v[80:83]
	v_mfma_f32_16x16x32_bf16 v[52:55], v[202:205], v[242:245], v[52:55]
	v_mfma_f32_16x16x32_bf16 v[44:47], v[210:213], v[242:245], v[44:47]
	s_setprio 0
	s_barrier
	s_mov_b32 m0, s41
	v_lshl_add_u64 v[166:167], s[14:15], 0, v[168:169]
	s_add_u32 s36, s14, 0x40000
	ds_read_b128 v[214:217], v137 offset:16384
	ds_read_b128 v[218:221], v137 offset:17408
	ds_read_b128 v[222:225], v137 offset:18432
	ds_read_b128 v[226:229], v137 offset:19456
	ds_read_b128 v[230:233], v137 offset:20480
	ds_read_b128 v[234:237], v137 offset:21504
	ds_read_b128 v[238:241], v137 offset:22528
	ds_read_b128 v[242:245], v137 offset:23552
	global_load_lds_dwordx4 v[166:167], off
	v_lshl_add_u64 v[246:247], s[14:15], 0, v[128:129]
	s_mov_b32 m0, s59
	s_addc_u32 s37, s15, 0
	global_load_lds_dwordx4 v[246:247], off
	v_lshl_add_u64 v[248:249], s[36:37], 0, v[168:169]
	s_mov_b32 m0, s95
	v_lshl_add_u64 v[250:251], s[26:27], 0, v[128:129]
	global_load_lds_dwordx4 v[248:249], off
	v_lshl_add_u64 v[248:249], s[36:37], 0, v[128:129]
	s_mov_b32 m0, vcc_lo
	s_nop 0
	global_load_lds_dwordx4 v[248:249], off
	v_lshl_add_u64 v[248:249], s[26:27], 0, v[168:169]
	s_mov_b32 m0, s94
	s_nop 0
	global_load_lds_dwordx4 v[248:249], off
	s_mov_b32 m0, vcc_hi
	s_nop 0
	global_load_lds_dwordx4 v[250:251], off
	s_waitcnt vmcnt(8)
	s_waitcnt lgkmcnt(0)
	s_barrier
	s_setprio 1
	s_waitcnt lgkmcnt(0)
	v_mfma_f32_16x16x32_bf16 v[68:71], v[154:157], v[214:217], v[68:71]
	v_mfma_f32_16x16x32_bf16 v[64:67], v[162:165], v[214:217], v[64:67]
	v_mfma_f32_16x16x32_bf16 v[60:63], v[154:157], v[222:225], v[60:63]
	v_mfma_f32_16x16x32_bf16 v[56:59], v[162:165], v[222:225], v[56:59]
	v_mfma_f32_16x16x32_bf16 v[48:51], v[154:157], v[230:233], v[48:51]
	v_mfma_f32_16x16x32_bf16 v[40:43], v[162:165], v[230:233], v[40:43]
	v_mfma_f32_16x16x32_bf16 v[36:39], v[154:157], v[238:241], v[36:39]
	v_mfma_f32_16x16x32_bf16 v[32:35], v[162:165], v[238:241], v[32:35]
	v_mfma_f32_16x16x32_bf16 v[68:71], v[158:161], v[218:221], v[68:71]
	v_mfma_f32_16x16x32_bf16 v[64:67], v[194:197], v[218:221], v[64:67]
	v_mfma_f32_16x16x32_bf16 v[60:63], v[158:161], v[226:229], v[60:63]
	v_mfma_f32_16x16x32_bf16 v[56:59], v[194:197], v[226:229], v[56:59]
	v_mfma_f32_16x16x32_bf16 v[48:51], v[158:161], v[234:237], v[48:51]
	v_mfma_f32_16x16x32_bf16 v[40:43], v[194:197], v[234:237], v[40:43]
	v_mfma_f32_16x16x32_bf16 v[36:39], v[158:161], v[242:245], v[36:39]
	v_mfma_f32_16x16x32_bf16 v[32:35], v[194:197], v[242:245], v[32:35]
	s_setprio 0
	s_setprio 1
	v_mfma_f32_16x16x32_bf16 v[28:31], v[198:201], v[214:217], v[28:31]
	v_mfma_f32_16x16x32_bf16 v[24:27], v[206:209], v[214:217], v[24:27]
	v_mfma_f32_16x16x32_bf16 v[20:23], v[198:201], v[222:225], v[20:23]
	v_mfma_f32_16x16x32_bf16 v[16:19], v[206:209], v[222:225], v[16:19]
	v_mfma_f32_16x16x32_bf16 v[12:15], v[198:201], v[230:233], v[12:15]
	v_mfma_f32_16x16x32_bf16 v[8:11], v[206:209], v[230:233], v[8:11]
	v_mfma_f32_16x16x32_bf16 v[4:7], v[198:201], v[238:241], v[4:7]
	v_mfma_f32_16x16x32_bf16 v[0:3], v[206:209], v[238:241], v[0:3]
	v_mfma_f32_16x16x32_bf16 v[28:31], v[202:205], v[218:221], v[28:31]
	v_mfma_f32_16x16x32_bf16 v[24:27], v[210:213], v[218:221], v[24:27]
	v_mfma_f32_16x16x32_bf16 v[20:23], v[202:205], v[226:229], v[20:23]
	v_mfma_f32_16x16x32_bf16 v[16:19], v[210:213], v[226:229], v[16:19]
	v_mfma_f32_16x16x32_bf16 v[12:15], v[202:205], v[234:237], v[12:15]
	v_mfma_f32_16x16x32_bf16 v[8:11], v[210:213], v[234:237], v[8:11]
	v_mfma_f32_16x16x32_bf16 v[4:7], v[202:205], v[242:245], v[4:7]
	v_mfma_f32_16x16x32_bf16 v[0:3], v[210:213], v[242:245], v[0:3]
	s_setprio 0
	s_barrier
	ds_read_b128 v[154:157], v146
	ds_read_b128 v[158:161], v147
	ds_read_b128 v[162:165], v148
	ds_read_b128 v[194:197], v149
	ds_read_b128 v[198:201], v150
	ds_read_b128 v[202:205], v151
	ds_read_b128 v[206:209], v152
	ds_read_b128 v[210:213], v153
	s_add_u32 s26, s26, 0x40000
	s_addc_u32 s27, s27, 0
	s_mov_b32 m0, s28
	v_lshl_add_u64 v[180:181], s[26:27], 0, v[168:169]
	ds_read_b128 v[214:217], v137 offset:32768
	ds_read_b128 v[218:221], v137 offset:33792
	ds_read_b128 v[222:225], v137 offset:34816
	ds_read_b128 v[226:229], v137 offset:35840
	ds_read_b128 v[230:233], v137 offset:36864
	ds_read_b128 v[234:237], v137 offset:37888
	ds_read_b128 v[238:241], v137 offset:38912
	ds_read_b128 v[242:245], v137 offset:39936
	global_load_lds_dwordx4 v[180:181], off
	v_lshl_add_u64 v[180:181], s[26:27], 0, v[128:129]
	s_mov_b32 m0, s29
	s_nop 0
	global_load_lds_dwordx4 v[180:181], off
	s_waitcnt vmcnt(8)
	s_waitcnt lgkmcnt(0)
	s_barrier
	s_setprio 1
	s_waitcnt lgkmcnt(0)
	v_mfma_f32_16x16x32_bf16 v[124:127], v[154:157], v[214:217], v[124:127]
	v_mfma_f32_16x16x32_bf16 v[120:123], v[162:165], v[214:217], v[120:123]
	v_mfma_f32_16x16x32_bf16 v[116:119], v[154:157], v[222:225], v[116:119]
	v_mfma_f32_16x16x32_bf16 v[112:115], v[162:165], v[222:225], v[112:115]
	v_mfma_f32_16x16x32_bf16 v[108:111], v[154:157], v[230:233], v[108:111]
	v_mfma_f32_16x16x32_bf16 v[104:107], v[162:165], v[230:233], v[104:107]
	v_mfma_f32_16x16x32_bf16 v[76:79], v[154:157], v[238:241], v[76:79]
	v_mfma_f32_16x16x32_bf16 v[72:75], v[162:165], v[238:241], v[72:75]
	v_mfma_f32_16x16x32_bf16 v[124:127], v[158:161], v[218:221], v[124:127]
	v_mfma_f32_16x16x32_bf16 v[120:123], v[194:197], v[218:221], v[120:123]
	v_mfma_f32_16x16x32_bf16 v[116:119], v[158:161], v[226:229], v[116:119]
	v_mfma_f32_16x16x32_bf16 v[112:115], v[194:197], v[226:229], v[112:115]
	v_mfma_f32_16x16x32_bf16 v[108:111], v[158:161], v[234:237], v[108:111]
	v_mfma_f32_16x16x32_bf16 v[104:107], v[194:197], v[234:237], v[104:107]
	v_mfma_f32_16x16x32_bf16 v[76:79], v[158:161], v[242:245], v[76:79]
	v_mfma_f32_16x16x32_bf16 v[72:75], v[194:197], v[242:245], v[72:75]
	s_setprio 0
	s_setprio 1
	v_mfma_f32_16x16x32_bf16 v[100:103], v[198:201], v[214:217], v[100:103]
	v_mfma_f32_16x16x32_bf16 v[96:99], v[206:209], v[214:217], v[96:99]
	v_mfma_f32_16x16x32_bf16 v[92:95], v[198:201], v[222:225], v[92:95]
	v_mfma_f32_16x16x32_bf16 v[88:91], v[206:209], v[222:225], v[88:91]
	v_mfma_f32_16x16x32_bf16 v[84:87], v[198:201], v[230:233], v[84:87]
	v_mfma_f32_16x16x32_bf16 v[80:83], v[206:209], v[230:233], v[80:83]
	v_mfma_f32_16x16x32_bf16 v[52:55], v[198:201], v[238:241], v[52:55]
	v_mfma_f32_16x16x32_bf16 v[44:47], v[206:209], v[238:241], v[44:47]
	v_mfma_f32_16x16x32_bf16 v[100:103], v[202:205], v[218:221], v[100:103]
	v_mfma_f32_16x16x32_bf16 v[96:99], v[210:213], v[218:221], v[96:99]
	v_mfma_f32_16x16x32_bf16 v[92:95], v[202:205], v[226:229], v[92:95]
	v_mfma_f32_16x16x32_bf16 v[88:91], v[210:213], v[226:229], v[88:91]
	v_mfma_f32_16x16x32_bf16 v[84:87], v[202:205], v[234:237], v[84:87]
	v_mfma_f32_16x16x32_bf16 v[80:83], v[210:213], v[234:237], v[80:83]
	v_mfma_f32_16x16x32_bf16 v[52:55], v[202:205], v[242:245], v[52:55]
	v_mfma_f32_16x16x32_bf16 v[44:47], v[210:213], v[242:245], v[44:47]
	s_setprio 0
	s_barrier
	s_mov_b32 m0, s19
	v_lshl_add_u64 v[166:167], v[166:167], 0, s[34:35]
	s_add_u32 s14, s14, 0x40080
	ds_read_b128 v[214:217], v137 offset:49152
	ds_read_b128 v[218:221], v137 offset:50176
	ds_read_b128 v[222:225], v137 offset:51200
	ds_read_b128 v[226:229], v137 offset:52224
	ds_read_b128 v[230:233], v137 offset:53248
	ds_read_b128 v[234:237], v137 offset:54272
	ds_read_b128 v[238:241], v137 offset:55296
	ds_read_b128 v[242:245], v137 offset:56320
	global_load_lds_dwordx4 v[166:167], off
	v_lshl_add_u64 v[166:167], v[246:247], 0, s[34:35]
	s_mov_b32 m0, s30
	s_addc_u32 s15, s15, 0
	global_load_lds_dwordx4 v[166:167], off
	v_lshl_add_u64 v[166:167], s[14:15], 0, v[168:169]
	s_mov_b32 m0, s63
	s_nop 0
	global_load_lds_dwordx4 v[166:167], off
	v_lshl_add_u64 v[166:167], s[14:15], 0, v[128:129]
	s_mov_b32 m0, s24
	s_nop 0
	global_load_lds_dwordx4 v[166:167], off
	v_lshl_add_u64 v[166:167], v[248:249], 0, s[34:35]
	s_mov_b32 m0, s61
	s_nop 0
	global_load_lds_dwordx4 v[166:167], off
	v_lshl_add_u64 v[166:167], v[250:251], 0, s[34:35]
	s_mov_b32 m0, s62
	s_nop 0
	global_load_lds_dwordx4 v[166:167], off
	s_waitcnt vmcnt(8)
	s_waitcnt lgkmcnt(0)
	s_barrier
	s_setprio 1
	s_waitcnt lgkmcnt(0)
	v_mfma_f32_16x16x32_bf16 v[68:71], v[154:157], v[214:217], v[68:71]
	v_mfma_f32_16x16x32_bf16 v[64:67], v[162:165], v[214:217], v[64:67]
	v_mfma_f32_16x16x32_bf16 v[60:63], v[154:157], v[222:225], v[60:63]
	v_mfma_f32_16x16x32_bf16 v[56:59], v[162:165], v[222:225], v[56:59]
	v_mfma_f32_16x16x32_bf16 v[48:51], v[154:157], v[230:233], v[48:51]
	v_mfma_f32_16x16x32_bf16 v[40:43], v[162:165], v[230:233], v[40:43]
	v_mfma_f32_16x16x32_bf16 v[36:39], v[154:157], v[238:241], v[36:39]
	v_mfma_f32_16x16x32_bf16 v[32:35], v[162:165], v[238:241], v[32:35]
	v_mfma_f32_16x16x32_bf16 v[68:71], v[158:161], v[218:221], v[68:71]
	v_mfma_f32_16x16x32_bf16 v[64:67], v[194:197], v[218:221], v[64:67]
	v_mfma_f32_16x16x32_bf16 v[60:63], v[158:161], v[226:229], v[60:63]
	v_mfma_f32_16x16x32_bf16 v[56:59], v[194:197], v[226:229], v[56:59]
	v_mfma_f32_16x16x32_bf16 v[48:51], v[158:161], v[234:237], v[48:51]
	v_mfma_f32_16x16x32_bf16 v[40:43], v[194:197], v[234:237], v[40:43]
	v_mfma_f32_16x16x32_bf16 v[36:39], v[158:161], v[242:245], v[36:39]
	v_mfma_f32_16x16x32_bf16 v[32:35], v[194:197], v[242:245], v[32:35]
	s_setprio 0
	s_setprio 1
	v_mfma_f32_16x16x32_bf16 v[28:31], v[198:201], v[214:217], v[28:31]
	v_mfma_f32_16x16x32_bf16 v[24:27], v[206:209], v[214:217], v[24:27]
	v_mfma_f32_16x16x32_bf16 v[20:23], v[198:201], v[222:225], v[20:23]
	v_mfma_f32_16x16x32_bf16 v[16:19], v[206:209], v[222:225], v[16:19]
	v_mfma_f32_16x16x32_bf16 v[12:15], v[198:201], v[230:233], v[12:15]
	v_mfma_f32_16x16x32_bf16 v[8:11], v[206:209], v[230:233], v[8:11]
	v_mfma_f32_16x16x32_bf16 v[4:7], v[198:201], v[238:241], v[4:7]
	v_mfma_f32_16x16x32_bf16 v[0:3], v[206:209], v[238:241], v[0:3]
	v_mfma_f32_16x16x32_bf16 v[28:31], v[202:205], v[218:221], v[28:31]
	v_mfma_f32_16x16x32_bf16 v[24:27], v[210:213], v[218:221], v[24:27]
	v_mfma_f32_16x16x32_bf16 v[20:23], v[202:205], v[226:229], v[20:23]
	v_mfma_f32_16x16x32_bf16 v[16:19], v[210:213], v[226:229], v[16:19]
	v_mfma_f32_16x16x32_bf16 v[12:15], v[202:205], v[234:237], v[12:15]
	v_mfma_f32_16x16x32_bf16 v[8:11], v[210:213], v[234:237], v[8:11]
	v_mfma_f32_16x16x32_bf16 v[4:7], v[202:205], v[242:245], v[4:7]
	v_mfma_f32_16x16x32_bf16 v[0:3], v[210:213], v[242:245], v[0:3]
	s_setprio 0
	s_barrier
	s_add_i32 s60, s60, 2
	s_add_u32 s88, s88, 0x100
	s_addc_u32 s89, s89, 0
	s_cmp_lt_u32 s60, 12
	s_cbranch_scc1 .LBB0_24
	ds_read_b128 v[154:157], v138
	ds_read_b128 v[158:161], v139
	ds_read_b128 v[162:165], v140
	ds_read_b128 v[194:197], v141
	ds_read_b128 v[198:201], v142
	ds_read_b128 v[202:205], v143
	ds_read_b128 v[206:209], v144
	ds_read_b128 v[210:213], v145
	s_add_u32 s14, s96, s88
	s_addc_u32 s15, s97, s89
	s_add_u32 s14, s14, 0x4000900
	s_addc_u32 s15, s15, 0
	s_add_u32 s36, s42, s88
	s_addc_u32 s37, s43, s89
	s_cmpk_eq_i32 s88, 0x700
	s_cselect_b32 s27, s87, s15
	s_cselect_b32 s26, s86, s14
	s_cselect_b32 s15, s85, s37
	s_cselect_b32 s14, s84, s36
	v_lshl_add_u64 v[166:167], v[130:131], 0, s[88:89]
	s_add_i32 m0, s94, 0xc000
	ds_read_b128 v[214:217], v137
	ds_read_b128 v[218:221], v137 offset:1024
	ds_read_b128 v[222:225], v137 offset:2048
	ds_read_b128 v[226:229], v137 offset:3072
	ds_read_b128 v[230:233], v137 offset:4096
	ds_read_b128 v[234:237], v137 offset:5120
	ds_read_b128 v[238:241], v137 offset:6144
	ds_read_b128 v[242:245], v137 offset:7168
	global_load_lds_dwordx4 v[166:167], off
	v_lshl_add_u64 v[166:167], v[132:133], 0, s[88:89]
	s_mov_b32 m0, s48
	s_nop 0
	global_load_lds_dwordx4 v[166:167], off
	s_waitcnt vmcnt(8)
	s_waitcnt lgkmcnt(0)
	s_barrier
	s_setprio 1
	s_waitcnt lgkmcnt(0)
	v_mfma_f32_16x16x32_bf16 v[124:127], v[154:157], v[214:217], v[124:127]
	v_mfma_f32_16x16x32_bf16 v[120:123], v[162:165], v[214:217], v[120:123]
	v_mfma_f32_16x16x32_bf16 v[116:119], v[154:157], v[222:225], v[116:119]
	v_mfma_f32_16x16x32_bf16 v[112:115], v[162:165], v[222:225], v[112:115]
	v_mfma_f32_16x16x32_bf16 v[108:111], v[154:157], v[230:233], v[108:111]
	v_mfma_f32_16x16x32_bf16 v[104:107], v[162:165], v[230:233], v[104:107]
	v_mfma_f32_16x16x32_bf16 v[76:79], v[154:157], v[238:241], v[76:79]
	v_mfma_f32_16x16x32_bf16 v[72:75], v[162:165], v[238:241], v[72:75]
	v_mfma_f32_16x16x32_bf16 v[124:127], v[158:161], v[218:221], v[124:127]
	v_mfma_f32_16x16x32_bf16 v[120:123], v[194:197], v[218:221], v[120:123]
	v_mfma_f32_16x16x32_bf16 v[116:119], v[158:161], v[226:229], v[116:119]
	v_mfma_f32_16x16x32_bf16 v[112:115], v[194:197], v[226:229], v[112:115]
	v_mfma_f32_16x16x32_bf16 v[108:111], v[158:161], v[234:237], v[108:111]
	v_mfma_f32_16x16x32_bf16 v[104:107], v[194:197], v[234:237], v[104:107]
	v_mfma_f32_16x16x32_bf16 v[76:79], v[158:161], v[242:245], v[76:79]
	v_mfma_f32_16x16x32_bf16 v[72:75], v[194:197], v[242:245], v[72:75]
	s_setprio 0
	s_setprio 1
	v_mfma_f32_16x16x32_bf16 v[100:103], v[198:201], v[214:217], v[100:103]
	v_mfma_f32_16x16x32_bf16 v[96:99], v[206:209], v[214:217], v[96:99]
	v_mfma_f32_16x16x32_bf16 v[92:95], v[198:201], v[222:225], v[92:95]
	v_mfma_f32_16x16x32_bf16 v[88:91], v[206:209], v[222:225], v[88:91]
	v_mfma_f32_16x16x32_bf16 v[84:87], v[198:201], v[230:233], v[84:87]
	v_mfma_f32_16x16x32_bf16 v[80:83], v[206:209], v[230:233], v[80:83]
	v_mfma_f32_16x16x32_bf16 v[52:55], v[198:201], v[238:241], v[52:55]
	v_mfma_f32_16x16x32_bf16 v[44:47], v[206:209], v[238:241], v[44:47]
	v_mfma_f32_16x16x32_bf16 v[100:103], v[202:205], v[218:221], v[100:103]
	v_mfma_f32_16x16x32_bf16 v[96:99], v[210:213], v[218:221], v[96:99]
	v_mfma_f32_16x16x32_bf16 v[92:95], v[202:205], v[226:229], v[92:95]
	v_mfma_f32_16x16x32_bf16 v[88:91], v[210:213], v[226:229], v[88:91]
	v_mfma_f32_16x16x32_bf16 v[84:87], v[202:205], v[234:237], v[84:87]
	v_mfma_f32_16x16x32_bf16 v[80:83], v[210:213], v[234:237], v[80:83]
	v_mfma_f32_16x16x32_bf16 v[52:55], v[202:205], v[242:245], v[52:55]
	v_mfma_f32_16x16x32_bf16 v[44:47], v[210:213], v[242:245], v[44:47]
	s_setprio 0
	s_barrier
	s_mov_b32 m0, s41
	v_lshl_add_u64 v[166:167], s[14:15], 0, v[168:169]
	s_add_u32 s36, s14, 0x40000
	ds_read_b128 v[214:217], v137 offset:16384
	ds_read_b128 v[218:221], v137 offset:17408
	ds_read_b128 v[222:225], v137 offset:18432
	ds_read_b128 v[226:229], v137 offset:19456
	ds_read_b128 v[230:233], v137 offset:20480
	ds_read_b128 v[234:237], v137 offset:21504
	ds_read_b128 v[238:241], v137 offset:22528
	ds_read_b128 v[242:245], v137 offset:23552
	v_lshl_add_u64 v[246:247], s[14:15], 0, v[128:129]
	s_mov_b32 m0, s59
	s_addc_u32 s37, s15, 0
	v_lshl_add_u64 v[248:249], s[36:37], 0, v[168:169]
	s_mov_b32 m0, s95
	v_lshl_add_u64 v[250:251], s[26:27], 0, v[128:129]
	v_lshl_add_u64 v[248:249], s[36:37], 0, v[128:129]
	s_mov_b32 m0, vcc_lo
	s_nop 0
	v_lshl_add_u64 v[248:249], s[26:27], 0, v[168:169]
	s_mov_b32 m0, s94
	s_nop 0
	s_mov_b32 m0, vcc_hi
	s_nop 0
	s_waitcnt vmcnt(2)
	s_waitcnt lgkmcnt(0)
	s_barrier
	s_setprio 1
	s_waitcnt lgkmcnt(0)
	v_mfma_f32_16x16x32_bf16 v[68:71], v[154:157], v[214:217], v[68:71]
	v_mfma_f32_16x16x32_bf16 v[64:67], v[162:165], v[214:217], v[64:67]
	v_mfma_f32_16x16x32_bf16 v[60:63], v[154:157], v[222:225], v[60:63]
	v_mfma_f32_16x16x32_bf16 v[56:59], v[162:165], v[222:225], v[56:59]
	v_mfma_f32_16x16x32_bf16 v[48:51], v[154:157], v[230:233], v[48:51]
	v_mfma_f32_16x16x32_bf16 v[40:43], v[162:165], v[230:233], v[40:43]
	v_mfma_f32_16x16x32_bf16 v[36:39], v[154:157], v[238:241], v[36:39]
	v_mfma_f32_16x16x32_bf16 v[32:35], v[162:165], v[238:241], v[32:35]
	v_mfma_f32_16x16x32_bf16 v[68:71], v[158:161], v[218:221], v[68:71]
	v_mfma_f32_16x16x32_bf16 v[64:67], v[194:197], v[218:221], v[64:67]
	v_mfma_f32_16x16x32_bf16 v[60:63], v[158:161], v[226:229], v[60:63]
	v_mfma_f32_16x16x32_bf16 v[56:59], v[194:197], v[226:229], v[56:59]
	v_mfma_f32_16x16x32_bf16 v[48:51], v[158:161], v[234:237], v[48:51]
	v_mfma_f32_16x16x32_bf16 v[40:43], v[194:197], v[234:237], v[40:43]
	v_mfma_f32_16x16x32_bf16 v[36:39], v[158:161], v[242:245], v[36:39]
	v_mfma_f32_16x16x32_bf16 v[32:35], v[194:197], v[242:245], v[32:35]
	s_setprio 0
	s_setprio 1
	v_mfma_f32_16x16x32_bf16 v[28:31], v[198:201], v[214:217], v[28:31]
	v_mfma_f32_16x16x32_bf16 v[24:27], v[206:209], v[214:217], v[24:27]
	v_mfma_f32_16x16x32_bf16 v[20:23], v[198:201], v[222:225], v[20:23]
	v_mfma_f32_16x16x32_bf16 v[16:19], v[206:209], v[222:225], v[16:19]
	v_mfma_f32_16x16x32_bf16 v[12:15], v[198:201], v[230:233], v[12:15]
	v_mfma_f32_16x16x32_bf16 v[8:11], v[206:209], v[230:233], v[8:11]
	v_mfma_f32_16x16x32_bf16 v[4:7], v[198:201], v[238:241], v[4:7]
	v_mfma_f32_16x16x32_bf16 v[0:3], v[206:209], v[238:241], v[0:3]
	v_mfma_f32_16x16x32_bf16 v[28:31], v[202:205], v[218:221], v[28:31]
	v_mfma_f32_16x16x32_bf16 v[24:27], v[210:213], v[218:221], v[24:27]
	v_mfma_f32_16x16x32_bf16 v[20:23], v[202:205], v[226:229], v[20:23]
	v_mfma_f32_16x16x32_bf16 v[16:19], v[210:213], v[226:229], v[16:19]
	v_mfma_f32_16x16x32_bf16 v[12:15], v[202:205], v[234:237], v[12:15]
	v_mfma_f32_16x16x32_bf16 v[8:11], v[210:213], v[234:237], v[8:11]
	v_mfma_f32_16x16x32_bf16 v[4:7], v[202:205], v[242:245], v[4:7]
	v_mfma_f32_16x16x32_bf16 v[0:3], v[210:213], v[242:245], v[0:3]
	s_setprio 0
	s_barrier
	ds_read_b128 v[154:157], v146
	ds_read_b128 v[158:161], v147
	ds_read_b128 v[162:165], v148
	ds_read_b128 v[194:197], v149
	ds_read_b128 v[198:201], v150
	ds_read_b128 v[202:205], v151
	ds_read_b128 v[206:209], v152
	ds_read_b128 v[210:213], v153
	s_add_u32 s26, s26, 0x40000
	s_addc_u32 s27, s27, 0
	s_mov_b32 m0, s28
	v_lshl_add_u64 v[180:181], s[26:27], 0, v[168:169]
	ds_read_b128 v[214:217], v137 offset:32768
	ds_read_b128 v[218:221], v137 offset:33792
	ds_read_b128 v[222:225], v137 offset:34816
	ds_read_b128 v[226:229], v137 offset:35840
	ds_read_b128 v[230:233], v137 offset:36864
	ds_read_b128 v[234:237], v137 offset:37888
	ds_read_b128 v[238:241], v137 offset:38912
	ds_read_b128 v[242:245], v137 offset:39936
	v_lshl_add_u64 v[180:181], s[26:27], 0, v[128:129]
	s_mov_b32 m0, s29
	s_nop 0
	s_waitcnt vmcnt(0)
	s_waitcnt lgkmcnt(0)
	s_barrier
	s_setprio 1
	s_waitcnt lgkmcnt(0)
	v_mfma_f32_16x16x32_bf16 v[124:127], v[154:157], v[214:217], v[124:127]
	v_mfma_f32_16x16x32_bf16 v[120:123], v[162:165], v[214:217], v[120:123]
	v_mfma_f32_16x16x32_bf16 v[116:119], v[154:157], v[222:225], v[116:119]
	v_mfma_f32_16x16x32_bf16 v[112:115], v[162:165], v[222:225], v[112:115]
	v_mfma_f32_16x16x32_bf16 v[108:111], v[154:157], v[230:233], v[108:111]
	v_mfma_f32_16x16x32_bf16 v[104:107], v[162:165], v[230:233], v[104:107]
	v_mfma_f32_16x16x32_bf16 v[76:79], v[154:157], v[238:241], v[76:79]
	v_mfma_f32_16x16x32_bf16 v[72:75], v[162:165], v[238:241], v[72:75]
	v_mfma_f32_16x16x32_bf16 v[124:127], v[158:161], v[218:221], v[124:127]
	v_mfma_f32_16x16x32_bf16 v[120:123], v[194:197], v[218:221], v[120:123]
	v_mfma_f32_16x16x32_bf16 v[116:119], v[158:161], v[226:229], v[116:119]
	v_mfma_f32_16x16x32_bf16 v[112:115], v[194:197], v[226:229], v[112:115]
	v_mfma_f32_16x16x32_bf16 v[108:111], v[158:161], v[234:237], v[108:111]
	v_mfma_f32_16x16x32_bf16 v[104:107], v[194:197], v[234:237], v[104:107]
	v_mfma_f32_16x16x32_bf16 v[76:79], v[158:161], v[242:245], v[76:79]
	v_mfma_f32_16x16x32_bf16 v[72:75], v[194:197], v[242:245], v[72:75]
	s_setprio 0
	s_setprio 1
	v_mfma_f32_16x16x32_bf16 v[100:103], v[198:201], v[214:217], v[100:103]
	v_mfma_f32_16x16x32_bf16 v[96:99], v[206:209], v[214:217], v[96:99]
	v_mfma_f32_16x16x32_bf16 v[92:95], v[198:201], v[222:225], v[92:95]
	v_mfma_f32_16x16x32_bf16 v[88:91], v[206:209], v[222:225], v[88:91]
	v_mfma_f32_16x16x32_bf16 v[84:87], v[198:201], v[230:233], v[84:87]
	v_mfma_f32_16x16x32_bf16 v[80:83], v[206:209], v[230:233], v[80:83]
	v_mfma_f32_16x16x32_bf16 v[52:55], v[198:201], v[238:241], v[52:55]
	v_mfma_f32_16x16x32_bf16 v[44:47], v[206:209], v[238:241], v[44:47]
	v_mfma_f32_16x16x32_bf16 v[100:103], v[202:205], v[218:221], v[100:103]
	v_mfma_f32_16x16x32_bf16 v[96:99], v[210:213], v[218:221], v[96:99]
	v_mfma_f32_16x16x32_bf16 v[92:95], v[202:205], v[226:229], v[92:95]
	v_mfma_f32_16x16x32_bf16 v[88:91], v[210:213], v[226:229], v[88:91]
	v_mfma_f32_16x16x32_bf16 v[84:87], v[202:205], v[234:237], v[84:87]
	v_mfma_f32_16x16x32_bf16 v[80:83], v[210:213], v[234:237], v[80:83]
	v_mfma_f32_16x16x32_bf16 v[52:55], v[202:205], v[242:245], v[52:55]
	v_mfma_f32_16x16x32_bf16 v[44:47], v[210:213], v[242:245], v[44:47]
	s_setprio 0
	s_barrier
	s_mov_b32 m0, s19
	v_lshl_add_u64 v[166:167], v[166:167], 0, s[34:35]
	s_add_u32 s14, s14, 0x40080
	ds_read_b128 v[214:217], v137 offset:49152
	ds_read_b128 v[218:221], v137 offset:50176
	ds_read_b128 v[222:225], v137 offset:51200
	ds_read_b128 v[226:229], v137 offset:52224
	ds_read_b128 v[230:233], v137 offset:53248
	ds_read_b128 v[234:237], v137 offset:54272
	ds_read_b128 v[238:241], v137 offset:55296
	ds_read_b128 v[242:245], v137 offset:56320
	v_lshl_add_u64 v[166:167], v[246:247], 0, s[34:35]
	s_mov_b32 m0, s30
	s_addc_u32 s15, s15, 0
	v_lshl_add_u64 v[166:167], s[14:15], 0, v[168:169]
	s_mov_b32 m0, s63
	s_nop 0
	v_lshl_add_u64 v[166:167], s[14:15], 0, v[128:129]
	s_mov_b32 m0, s24
	s_nop 0
	v_lshl_add_u64 v[166:167], v[248:249], 0, s[34:35]
	s_mov_b32 m0, s61
	s_nop 0
	v_lshl_add_u64 v[166:167], v[250:251], 0, s[34:35]
	s_mov_b32 m0, s62
	s_nop 0
	s_waitcnt vmcnt(0)
	s_waitcnt lgkmcnt(0)
	s_barrier
	s_setprio 1
	s_waitcnt lgkmcnt(0)
	v_mfma_f32_16x16x32_bf16 v[68:71], v[154:157], v[214:217], v[68:71]
	v_mfma_f32_16x16x32_bf16 v[64:67], v[162:165], v[214:217], v[64:67]
	v_mfma_f32_16x16x32_bf16 v[60:63], v[154:157], v[222:225], v[60:63]
	v_mfma_f32_16x16x32_bf16 v[56:59], v[162:165], v[222:225], v[56:59]
	v_mfma_f32_16x16x32_bf16 v[48:51], v[154:157], v[230:233], v[48:51]
	v_mfma_f32_16x16x32_bf16 v[40:43], v[162:165], v[230:233], v[40:43]
	v_mfma_f32_16x16x32_bf16 v[36:39], v[154:157], v[238:241], v[36:39]
	v_mfma_f32_16x16x32_bf16 v[32:35], v[162:165], v[238:241], v[32:35]
	v_mfma_f32_16x16x32_bf16 v[68:71], v[158:161], v[218:221], v[68:71]
	v_mfma_f32_16x16x32_bf16 v[64:67], v[194:197], v[218:221], v[64:67]
	v_mfma_f32_16x16x32_bf16 v[60:63], v[158:161], v[226:229], v[60:63]
	v_mfma_f32_16x16x32_bf16 v[56:59], v[194:197], v[226:229], v[56:59]
	v_mfma_f32_16x16x32_bf16 v[48:51], v[158:161], v[234:237], v[48:51]
	v_mfma_f32_16x16x32_bf16 v[40:43], v[194:197], v[234:237], v[40:43]
	v_mfma_f32_16x16x32_bf16 v[36:39], v[158:161], v[242:245], v[36:39]
	v_mfma_f32_16x16x32_bf16 v[32:35], v[194:197], v[242:245], v[32:35]
	s_setprio 0
	s_setprio 1
	v_mfma_f32_16x16x32_bf16 v[28:31], v[198:201], v[214:217], v[28:31]
	v_mfma_f32_16x16x32_bf16 v[24:27], v[206:209], v[214:217], v[24:27]
	v_mfma_f32_16x16x32_bf16 v[20:23], v[198:201], v[222:225], v[20:23]
	v_mfma_f32_16x16x32_bf16 v[16:19], v[206:209], v[222:225], v[16:19]
	v_mfma_f32_16x16x32_bf16 v[12:15], v[198:201], v[230:233], v[12:15]
	v_mfma_f32_16x16x32_bf16 v[8:11], v[206:209], v[230:233], v[8:11]
	v_mfma_f32_16x16x32_bf16 v[4:7], v[198:201], v[238:241], v[4:7]
	v_mfma_f32_16x16x32_bf16 v[0:3], v[206:209], v[238:241], v[0:3]
	v_mfma_f32_16x16x32_bf16 v[28:31], v[202:205], v[218:221], v[28:31]
	v_mfma_f32_16x16x32_bf16 v[24:27], v[210:213], v[218:221], v[24:27]
	v_mfma_f32_16x16x32_bf16 v[20:23], v[202:205], v[226:229], v[20:23]
	v_mfma_f32_16x16x32_bf16 v[16:19], v[210:213], v[226:229], v[16:19]
	v_mfma_f32_16x16x32_bf16 v[12:15], v[202:205], v[234:237], v[12:15]
	v_mfma_f32_16x16x32_bf16 v[8:11], v[210:213], v[234:237], v[8:11]
	v_mfma_f32_16x16x32_bf16 v[4:7], v[202:205], v[242:245], v[4:7]
	v_mfma_f32_16x16x32_bf16 v[0:3], v[210:213], v[242:245], v[0:3]
	s_setprio 0
	s_barrier
	s_add_i32 s60, s60, 2
	s_add_u32 s88, s88, 0x100
	s_addc_u32 s89, s89, 0
	s_cmp_lt_u32 s60, 14
	v_lshrrev_b32_e32 v248, 1, v192
	v_and_b32_e32 v249, 1, v192
	v_lshlrev_b32_e32 v248, 11, v248
	v_lshl_or_b32 v248, v249, 7, v248
	v_add_u32_e32 v248, 0x3f8000, v248
	v_mov_b32_e32 v249, 0
	v_lshl_add_u64 v[248:249], s[86:87], 0, v[248:249]
	s_waitcnt vmcnt(0)
	s_cmpk_gt_u32 s92, 0xff
	s_cbranch_scc1 .LBB0_27
	s_barrier

.LBB0_29:
	s_or_b64 exec, exec, s[14:15]
	v_mov_b32_e32 v114, v192
	s_waitcnt lgkmcnt(0)
	s_barrier
	s_lshl_b32 s26, s40, 7
	v_lshlrev_b32_e32 v80, 3, v114
	v_and_b32_e32 v115, 0x78, v80
	v_or_b32_e32 v112, s26, v115
	v_ashrrev_i32_e32 v113, 31, v112
	s_mov_b64 s[52:53], s[44:45]
	v_readlane_b32 s44, v255, 16
	v_lshlrev_b64 v[92:93], 2, v[112:113]
	v_readlane_b32 s45, v255, 17
	v_lshl_add_u64 v[84:85], s[56:57], 0, v[92:93]
	v_lshl_add_u64 v[88:89], s[52:53], 0, v[92:93]
	v_lshl_add_u64 v[94:95], s[44:45], 0, v[92:93]
	v_lshl_add_u64 v[108:109], s[48:49], 0, v[92:93]
	global_load_dwordx4 v[80:83], v[84:85], off offset:16
	global_load_dwordx4 v[96:99], v[84:85], off
	s_nop 0
	global_load_dwordx4 v[84:87], v[88:89], off offset:16
	global_load_dwordx4 v[100:103], v[88:89], off
	s_nop 0
	global_load_dwordx4 v[88:91], v[94:95], off offset:16
	global_load_dwordx4 v[104:107], v[94:95], off
	s_nop 0
	global_load_dwordx4 v[92:95], v[108:109], off offset:16
	s_nop 0
	global_load_dwordx4 v[108:111], v[108:109], off
	v_ashrrev_i32_e32 v116, 4, v114
	v_lshrrev_b32_e32 v114, 4, v114
	v_bfi_b32 v118, -4, v116, v114
	s_movk_i32 s5, 0x7f
	v_add_u32_e32 v114, s91, v118
	v_cmp_gt_i32_e32 vcc, s5, v118
	s_mov_b32 s5, 0x14000
	v_cmp_gt_i32_e64 s[40:41], s5, v114
	s_movk_i32 s5, 0x410
	v_lshlrev_b32_e32 v116, 2, v115
	v_mul_lo_u32 v117, v118, s5
	s_and_b64 s[28:29], vcc, s[40:41]
	v_add_u32_e32 v120, v116, v117
	v_lshl_add_u32 v119, v115, 2, v117
	s_and_saveexec_b64 s[14:15], s[28:29]
	s_mov_b32 s92, 0
	s_mov_b32 s93, 0x403e0000
	s_cbranch_execz .LBB0_31
	v_cmp_gt_i32_e32 vcc, s33, v114
	ds_read_b128 v[122:125], v120
	ds_read_b128 v[130:133], v120 offset:16
	ds_read_b128 v[136:139], v119 offset:1040
	ds_read_b128 v[140:143], v119 offset:1056
	ds_read_b128 v[144:147], v119 offset:2080
	ds_read_b128 v[148:151], v119 offset:2096
	ds_read_b128 v[152:155], v119 offset:1552
	ds_read_b128 v[156:159], v119 offset:1568
	v_cndmask_b32_e32 v115, v178, v179, vcc
	v_and_b32_e32 v115, v115, v114
	v_cndmask_b32_e32 v121, v175, v176, vcc
	v_cmp_ne_u32_e32 vcc, 0, v115
	v_add_u32_e32 v115, 1, v115
	s_mov_b32 s24, 0xc0135761
	s_waitcnt lgkmcnt(6)
	v_cndmask_b32_e32 v127, 0, v133, vcc
	v_cndmask_b32_e32 v126, 0, v132, vcc
	v_cndmask_b32_e32 v131, 0, v131, vcc
	v_cndmask_b32_e32 v130, 0, v130, vcc
	v_cndmask_b32_e32 v125, 0, v125, vcc
	v_cndmask_b32_e32 v124, 0, v124, vcc
	v_cndmask_b32_e32 v123, 0, v123, vcc
	v_cndmask_b32_e32 v122, 0, v122, vcc
	v_cmp_lt_u32_e32 vcc, v115, v121
	v_ashrrev_i32_e32 v115, 31, v114
	v_lshlrev_b64 v[114:115], 13, v[114:115]
	s_waitcnt lgkmcnt(3)
	v_cndmask_b32_e32 v145, 0, v145, vcc
	v_cndmask_b32_e32 v144, 0, v144, vcc
	s_waitcnt vmcnt(0)
	global_load_dword v250, v[248:249], off
	v_pk_fma_f32 v[144:145], v[104:105], v[144:145], v[108:109]
	v_cndmask_b32_e32 v147, 0, v147, vcc
	v_pk_fma_f32 v[136:137], v[100:101], v[136:137], v[144:145]
	v_mov_b64_e32 v[144:145], s[24:25]
	v_pk_fma_f32 v[122:123], v[96:97], v[122:123], v[136:137]
	s_mov_b32 s24, 0x3dd2d3e8
	v_pk_mul_f32 v[136:137], v[122:123], v[122:123]
	v_cndmask_b32_e32 v146, 0, v146, vcc
	v_pk_fma_f32 v[136:137], v[136:137], s[24:25], v[144:145] op_sel_hi:[1,0,0] neg_lo:[1,0,0] neg_hi:[1,0,0]
	s_waitcnt lgkmcnt(2)
	v_cndmask_b32_e32 v133, 0, v151, vcc
	v_pk_mul_f32 v[136:137], v[122:123], v[136:137]
	v_cndmask_b32_e32 v132, 0, v150, vcc
	v_exp_f32_e32 v136, v136
	v_exp_f32_e32 v137, v137
	v_cndmask_b32_e32 v149, 0, v149, vcc
	v_cndmask_b32_e32 v148, 0, v148, vcc
	v_pk_fma_f32 v[132:133], v[90:91], v[132:133], v[94:95]
	v_pk_add_f32 v[136:137], v[136:137], 1.0 op_sel_hi:[1,0]
	v_pk_fma_f32 v[132:133], v[86:87], v[142:143], v[132:133]
	v_rcp_f32_e32 v136, v136
	v_rcp_f32_e32 v137, v137
	v_pk_fma_f32 v[126:127], v[82:83], v[126:127], v[132:133]
	v_lshl_add_u64 v[114:115], s[46:47], 0, v[114:115]
	v_pk_mul_f32 v[132:133], v[126:127], v[126:127]
	v_pk_mul_f32 v[122:123], v[122:123], v[136:137]
	v_pk_fma_f32 v[136:137], v[106:107], v[146:147], v[110:111]
	v_pk_fma_f32 v[132:133], v[132:133], s[24:25], v[144:145] op_sel_hi:[1,0,0] neg_lo:[1,0,0] neg_hi:[1,0,0]
	v_pk_fma_f32 v[136:137], v[102:103], v[138:139], v[136:137]
	v_pk_mul_f32 v[132:133], v[126:127], v[132:133]
	v_pk_fma_f32 v[124:125], v[98:99], v[124:125], v[136:137]
	v_exp_f32_e32 v132, v132
	v_pk_mul_f32 v[136:137], v[124:125], v[124:125]
	v_exp_f32_e32 v133, v133
	v_pk_fma_f32 v[136:137], v[136:137], s[24:25], v[144:145] op_sel_hi:[1,0,0] neg_lo:[1,0,0] neg_hi:[1,0,0]
	s_waitcnt lgkmcnt(1)
	v_pk_mul_f32 v[122:123], v[152:153], v[122:123]
	v_pk_mul_f32 v[136:137], v[124:125], v[136:137]
	v_pk_add_f32 v[132:133], v[132:133], 1.0 op_sel_hi:[1,0]
	v_exp_f32_e32 v136, v136
	v_exp_f32_e32 v137, v137
	v_rcp_f32_e32 v132, v132
	v_rcp_f32_e32 v133, v133
	v_cvt_pk_bf16_f32 v122, v122, v123
	v_pk_add_f32 v[136:137], v[136:137], 1.0 op_sel_hi:[1,0]
	v_lshl_add_u64 v[114:115], v[112:113], 1, v[114:115]
	v_rcp_f32_e32 v136, v136
	v_rcp_f32_e32 v137, v137
	v_pk_mul_f32 v[126:127], v[126:127], v[132:133]
	v_pk_mul_f32 v[124:125], v[124:125], v[136:137]
	v_pk_fma_f32 v[136:137], v[88:89], v[148:149], v[92:93]
	v_pk_mul_f32 v[124:125], v[154:155], v[124:125]
	v_pk_fma_f32 v[136:137], v[84:85], v[140:141], v[136:137]
	s_waitcnt lgkmcnt(0)
	v_pk_mul_f32 v[126:127], v[158:159], v[126:127]
	v_pk_fma_f32 v[130:131], v[80:81], v[130:131], v[136:137]
	v_cvt_pk_bf16_f32 v123, v124, v125
	v_pk_mul_f32 v[136:137], v[130:131], v[130:131]
	v_cvt_pk_bf16_f32 v125, v126, v127
	v_pk_fma_f32 v[136:137], v[136:137], s[24:25], v[144:145] op_sel_hi:[1,0,0] neg_lo:[1,0,0] neg_hi:[1,0,0]
	s_nop 0
	v_pk_mul_f32 v[136:137], v[130:131], v[136:137]
	s_nop 0
	v_exp_f32_e32 v136, v136
	v_exp_f32_e32 v137, v137
	s_nop 0
	v_pk_add_f32 v[136:137], v[136:137], 1.0 op_sel_hi:[1,0]
	s_nop 0
	v_rcp_f32_e32 v136, v136
	v_rcp_f32_e32 v137, v137
	s_nop 0
	v_pk_mul_f32 v[130:131], v[130:131], v[136:137]
	s_nop 0
	v_pk_mul_f32 v[130:131], v[156:157], v[130:131]
	s_nop 0
	v_cvt_pk_bf16_f32 v124, v130, v131
	global_store_dwordx4 v[114:115], v[122:125], off

.Lp4_skip_b0:
	s_waitcnt vmcnt(0)
	s_branch .LBB0_41
	s_nop 0
	s_nop 0
	s_nop 0
	s_nop 0
	s_nop 0
	s_nop 0
	s_nop 0
	s_nop 0
